# scan loops: redundant store-drain waits removed from back-edge (load-covering waits kept); natten QK^T LDS reads software-pipelined
# baseline (speedup 1.0000x reference)
; #define GAS __attribute__((address_space(1)))
; __device__ __forceinline__ unsigned pk2(float lo, float hi) { const f32x2_t v = {lo, hi}; const bf16x2_t b = __builtin_convertvector(v, bf16x2_t); return __builtin_bit_cast(unsigned, b); }
; template <int DK> __device__ __forceinline__ void scan_state_unit(const ScanBufs<DK>& S, int unit, int lane, bool skip_ctx_store) {
;     ...
;         if (!(skip_ctx_store && s < 4)) {
;             bf16* sp = S.SP + (((((size_t)dir * NCH + g) * 8 + h) * (DK / 8) + dkb * 4) * 128 + dvb * 64 + r) * 8 + 4 * hi;
; #pragma unroll
;             for (int j = 0; j < 2; ++j)
; #pragma unroll
;                 for (int q = 0; q < 4; ++q) { v2u o; o.x = pk2(acc[j][4 * q], acc[j][4 * q + 1]); o.y = pk2(acc[j][4 * q + 2], acc[j][4 * q + 3]); *(GAS v2u*)(sp + ((size_t)q * 128 + j * 32) * 8) = o; }
;         }
; #pragma unroll
;         for (int j = 0; j < 2; ++j)
; #pragma unroll
;             for (int q = 0; q < 4; ++q)
; #pragma unroll
;                 for (int i = 0; i < 4; ++i) acc[j][4 * q + i] *= cur.ae[q][i];
.LBB0_916:
	s_add_i32 s6, s1, -1
	s_and_b64 s[2:3], s[78:79], exec
	s_cselect_b32 s2, s6, s0
	s_add_i32 s0, s0, -1
	s_add_i32 s8, s2, s59
	s_and_b64 s[2:3], s[78:79], exec
	s_cselect_b32 s2, s1, s0
	s_add_i32 s2, s2, s59
	s_ashr_i32 s3, s2, 31
	s_add_u32 s6, s2, s25
	s_nop 0
	v_cvt_pk_bf16_f32 v82, v0, v1
	v_cvt_pk_bf16_f32 v83, v2, v3
	v_cvt_pk_bf16_f32 v84, v4, v5
	v_cvt_pk_bf16_f32 v85, v6, v7
	v_cvt_pk_bf16_f32 v90, v8, v9
	v_cvt_pk_bf16_f32 v91, v10, v11
	v_cvt_pk_bf16_f32 v92, v12, v13
	v_cvt_pk_bf16_f32 v93, v14, v15
	v_cvt_pk_bf16_f32 v102, v16, v17
	v_cvt_pk_bf16_f32 v103, v18, v19
	v_cvt_pk_bf16_f32 v104, v20, v21
	v_cvt_pk_bf16_f32 v105, v22, v23
	v_cvt_pk_bf16_f32 v114, v24, v25
	v_cvt_pk_bf16_f32 v115, v26, v27
	v_cvt_pk_bf16_f32 v116, v28, v29
	v_cvt_pk_bf16_f32 v117, v30, v31
	s_waitcnt vmcnt(12)
	v_pk_mul_f32 v[0:1], v[138:139], v[0:1]
	v_pk_mul_f32 v[2:3], v[140:141], v[2:3]
	s_waitcnt vmcnt(8)
	v_pk_mul_f32 v[4:5], v[146:147], v[4:5]
	v_pk_mul_f32 v[6:7], v[148:149], v[6:7]
	v_pk_mul_f32 v[8:9], v[150:151], v[8:9]
	v_pk_mul_f32 v[10:11], v[152:153], v[10:11]

; #define GAS __attribute__((address_space(1)))
; __device__ __forceinline__ unsigned pk2(float lo, float hi) { const f32x2_t v = {lo, hi}; const bf16x2_t b = __builtin_convertvector(v, bf16x2_t); return __builtin_bit_cast(unsigned, b); }
; template <int DK> __device__ __forceinline__ void scan_state_unit(const ScanBufs<DK>& S, int unit, int lane, bool skip_ctx_store) {
;     ...
;         if (!(skip_ctx_store && s < 4)) {
;             bf16* sp = S.SP + (((((size_t)dir * NCH + g) * 8 + h) * (DK / 8) + dkb * 4) * 128 + dvb * 64 + r) * 8 + 4 * hi;
; #pragma unroll
;             for (int j = 0; j < 2; ++j)
; #pragma unroll
;                 for (int q = 0; q < 4; ++q) { v2u o; o.x = pk2(acc[j][4 * q], acc[j][4 * q + 1]); o.y = pk2(acc[j][4 * q + 2], acc[j][4 * q + 3]); *(GAS v2u*)(sp + ((size_t)q * 128 + j * 32) * 8) = o; }
;         }
; #pragma unroll
;         for (int j = 0; j < 2; ++j)
; #pragma unroll
;             for (int q = 0; q < 4; ++q)
; #pragma unroll
;                 for (int i = 0; i < 4; ++i) acc[j][4 * q + i] *= cur.ae[q][i];
.LBB0_931:
	s_add_i32 s4, s1, -1
	s_and_b64 s[2:3], s[26:27], exec
	s_cselect_b32 s2, s4, s0
	s_add_i32 s0, s0, -1
	s_add_i32 s6, s2, s63
	s_and_b64 s[2:3], s[26:27], exec
	s_cselect_b32 s2, s1, s0
	s_add_i32 s2, s2, s63
	s_ashr_i32 s3, s2, 31
	s_add_u32 s4, s2, s62
	s_addc_u32 s5, s3, 0
	s_lshl_b64 s[2:3], s[2:3], 17
	v_lshl_add_u64 v[66:67], v[54:55], 0, s[2:3]
	v_add_co_u32_e32 v74, vcc, s8, v66
	v_cvt_pk_bf16_f32 v56, v0, v1
	s_nop 0
	v_addc_co_u32_e32 v75, vcc, 0, v67, vcc
	v_cvt_pk_bf16_f32 v57, v2, v3
	v_cvt_pk_bf16_f32 v60, v4, v5
	v_cvt_pk_bf16_f32 v61, v6, v7
	v_cvt_pk_bf16_f32 v58, v8, v9
	v_cvt_pk_bf16_f32 v59, v10, v11
	v_cvt_pk_bf16_f32 v62, v12, v13
	v_cvt_pk_bf16_f32 v63, v14, v15
	v_cvt_pk_bf16_f32 v94, v16, v17
	v_cvt_pk_bf16_f32 v95, v18, v19
	v_cvt_pk_bf16_f32 v96, v20, v21
	v_cvt_pk_bf16_f32 v97, v22, v23
	v_cvt_pk_bf16_f32 v98, v24, v25
	v_cvt_pk_bf16_f32 v99, v26, v27
	v_cvt_pk_bf16_f32 v100, v28, v29
	v_cvt_pk_bf16_f32 v101, v30, v31
	s_waitcnt vmcnt(12)
	v_pk_mul_f32 v[0:1], v[138:139], v[0:1]
	v_pk_mul_f32 v[2:3], v[140:141], v[2:3]
	s_waitcnt vmcnt(8)
	v_pk_mul_f32 v[4:5], v[146:147], v[4:5]
	v_pk_mul_f32 v[6:7], v[148:149], v[6:7]
	v_pk_mul_f32 v[8:9], v[154:155], v[8:9]
	v_pk_mul_f32 v[10:11], v[156:157], v[10:11]
